# NA bias softmax: row sums computed once before PV from the f32 probabilities with packed f32 adds (two 7-op chains) instead of one fmac per element
# speedup vs baseline: 1.0304x; 1.0029x over previous
; template <int DQK, bool NA, bool SMAX, int LDV> ...
;     ...
;         if (NA && it >= 4) {
;           const int kr = rs + (it - 4);
;           const int ql = w * 32 + qt * 16 + fr, qr = r0 + (ql >> 6), qc = ql & 63;
;           const int rst = min(max(qr - 4, 0), 24);
;           const bool rowok = (kr >= rst) && (kr < rst + 8);
;           const int cst = min(max(qc - 8, 0), 48);
;           const int base = (kr - qr + 7) * 31 + 15 - qc;
;           float bv[4][4];
; #pragma unroll
;           for (int kt = 0; kt < 4; ++kt)
; #pragma unroll
;             for (int j = 0; j < 4; ++j) bv[kt][j] = rpbl[min(max(base + kt * 16 + fq * 4 + j, 0), 464)];
; #pragma unroll
;           for (int kt = 0; kt < 4; ++kt)
; #pragma unroll
;             for (int j = 0; j < 4; ++j) {
;               const int kc = kt * 16 + fq * 4 + j;
;               const float okf = (rowok && (kc >= cst) && (kc < cst + 16)) ? 1.f : 0.f;
;               const float pv = __builtin_amdgcn_exp2f(__builtin_fmaf(s[kt][qt][j], c1, bv[kt][j] - m0)) * okf;
;               s[kt][qt][j] = pv; sum += pv;
;             }
.LBB0_1069:
	s_andn2_b64 vcc, exec, s[26:27]
	s_cbranch_vccnz .LBB0_1071
	v_subrev_u32_e32 v0, 31, v208
	s_movk_i32 s101, 0x100
	v_lshl_add_u32 v211, v0, 2, s101
	ds_read_b32 v104, v211 offset:41728
	ds_read_b32 v105, v211 offset:41732
	ds_read_b32 v106, v211 offset:41736
	ds_read_b32 v107, v211 offset:41740
	ds_read_b32 v108, v211 offset:41792
	ds_read_b32 v109, v211 offset:41796
	ds_read_b32 v110, v211 offset:41800
	ds_read_b32 v111, v211 offset:41804
	ds_read_b32 v112, v211 offset:41856
	ds_read_b32 v113, v211 offset:41860
	ds_read_b32 v114, v211 offset:41864
	ds_read_b32 v115, v211 offset:41868
	ds_read_b32 v128, v211 offset:41920
	s_add_i32 s26, s19, s43
	s_add_i32 s26, s26, -4
	ds_read_b32 v129, v211 offset:41924
	v_cmp_ge_i32_e32 vcc, s26, v164
	v_cmp_lt_i32_e64 s[40:41], s26, v163
	s_waitcnt lgkmcnt(13)
	s_or_b64 s[26:27], s[40:41], vcc
	v_fmac_f32_e32 v104, 0x3e38aa3b, v144
	s_waitcnt lgkmcnt(12)
	s_or_b64 s[40:41], s[26:27], s[58:59]
	v_exp_f32_e32 v130, v104
	v_fmac_f32_e32 v105, 0x3e38aa3b, v145
	ds_read_b32 v2, v211 offset:41928
	ds_read_b32 v3, v211 offset:41932
	v_cndmask_b32_e64 v104, v130, 0, s[40:41]
	v_readlane_b32 s40, v248, 21
	v_exp_f32_e32 v131, v105
	v_readlane_b32 s41, v248, 22
	s_or_b64 s[40:41], s[26:27], s[40:41]
	s_waitcnt lgkmcnt(13)
	v_cndmask_b32_e64 v105, v131, 0, s[40:41]
	v_fmac_f32_e32 v106, 0x3e38aa3b, v146
	v_exp_f32_e32 v131, v106
	s_or_b64 s[40:41], s[26:27], s[52:53]
	s_waitcnt lgkmcnt(12)
	v_cndmask_b32_e64 v106, v131, 0, s[40:41]
	v_fmac_f32_e32 v107, 0x3e38aa3b, v147
	v_exp_f32_e32 v131, v107
	s_or_b64 s[40:41], s[26:27], s[54:55]
	s_waitcnt lgkmcnt(11)
	v_cndmask_b32_e64 v107, v131, 0, s[40:41]
	v_fmac_f32_e32 v108, 0x3e38aa3b, v140
	v_exp_f32_e32 v131, v108
	s_or_b64 s[40:41], s[26:27], s[56:57]
	s_waitcnt lgkmcnt(10)
	v_cndmask_b32_e64 v130, v165, 0, s[40:41]
	v_fmac_f32_e32 v109, 0x3e38aa3b, v141
	v_mul_f32_e32 v108, v130, v131
	v_exp_f32_e32 v131, v109
	s_or_b64 s[40:41], s[26:27], s[60:61]
	s_waitcnt lgkmcnt(9)
	v_cndmask_b32_e64 v130, v166, 0, s[40:41]
	v_fmac_f32_e32 v110, 0x3e38aa3b, v142
	v_mul_f32_e32 v109, v130, v131
	v_exp_f32_e32 v131, v110
	s_or_b64 s[40:41], s[26:27], s[50:51]
	s_waitcnt lgkmcnt(8)
	v_cndmask_b32_e64 v130, v168, 0, s[40:41]
	v_fmac_f32_e32 v111, 0x3e38aa3b, v143
	v_mul_f32_e32 v110, v130, v131
	v_exp_f32_e32 v131, v111
	s_or_b64 s[40:41], s[26:27], s[64:65]
	s_waitcnt lgkmcnt(7)
	v_cndmask_b32_e64 v130, v169, 0, s[40:41]
	v_fmac_f32_e32 v112, 0x3e38aa3b, v136
	v_mul_f32_e32 v111, v130, v131
	v_exp_f32_e32 v131, v112
	s_or_b64 s[40:41], s[26:27], s[66:67]
	s_waitcnt lgkmcnt(6)
	v_cndmask_b32_e64 v130, v170, 0, s[40:41]
	v_fmac_f32_e32 v113, 0x3e38aa3b, v137
	v_mul_f32_e32 v112, v130, v131
	v_exp_f32_e32 v131, v113
	s_or_b64 s[40:41], s[26:27], s[68:69]
	s_waitcnt lgkmcnt(5)
	v_cndmask_b32_e64 v130, v171, 0, s[40:41]
	v_fmac_f32_e32 v114, 0x3e38aa3b, v138
	v_mul_f32_e32 v113, v130, v131
	v_exp_f32_e32 v131, v114
	s_or_b64 s[40:41], s[26:27], s[70:71]
	s_waitcnt lgkmcnt(4)
	v_cndmask_b32_e64 v130, v172, 0, s[40:41]
	v_fmac_f32_e32 v115, 0x3e38aa3b, v139
	v_mul_f32_e32 v114, v130, v131
	v_exp_f32_e32 v131, v115
	s_or_b64 s[40:41], s[26:27], s[72:73]
	s_waitcnt lgkmcnt(3)
	v_cndmask_b32_e64 v130, v173, 0, s[40:41]
	v_fmac_f32_e32 v128, 0x3e38aa3b, v132
	v_mul_f32_e32 v115, v130, v131
	v_exp_f32_e32 v131, v128
	s_waitcnt lgkmcnt(2)
	v_cndmask_b32_e64 v130, v174, 0, s[26:27]
	v_fmac_f32_e32 v129, 0x3e38aa3b, v133
	s_waitcnt lgkmcnt(1)
	v_mul_f32_e32 v128, v130, v131
	v_exp_f32_e32 v131, v129
	v_fmac_f32_e32 v2, 0x3e38aa3b, v134
	s_waitcnt lgkmcnt(0)
	v_exp_f32_e32 v2, v2
	v_fmac_f32_e32 v3, 0x3e38aa3b, v135
	v_exp_f32_e32 v3, v3
	v_cndmask_b32_e64 v130, v175, 0, s[26:27]
	v_mul_f32_e32 v129, v130, v131
	v_cndmask_b32_e64 v131, v176, 0, s[26:27]
	v_mul_f32_e32 v130, v131, v2
	v_cndmask_b32_e64 v2, v177, 0, s[26:27]
	v_mul_f32_e32 v131, v2, v3

; DI unsigned cvt_pk_bf16(float lo, float hi) { f32x2_t v = {lo, hi}; bf16x2_t b = __builtin_convertvector(v, bf16x2_t); return __builtin_bit_cast(unsigned, b); }
; template <int DQK, bool NA, bool SMAX, int LDV> ...
;     ...
;           for (int kt = 0; kt < 4; ++kt)
; #pragma unroll
;             for (int j = 0; j < 4; ++j) bv[kt][j] = rpbl[min(max(base + kt * 16 + fq * 4 + j, 0), 464)];
; #pragma unroll
;           for (int kt = 0; kt < 4; ++kt)
; #pragma unroll
;             for (int j = 0; j < 4; ++j) {
;               const int kc = kt * 16 + fq * 4 + j;
;               const float okf = (rowok && (kc >= cst) && (kc < cst + 16)) ? 1.f : 0.f;
;               const float pv = __builtin_amdgcn_exp2f(__builtin_fmaf(s[kt][qt][j], c1, bv[kt][j] - m0)) * okf;
;               s[kt][qt][j] = pv; sum += pv;
;             }
;         } else {
; #pragma unroll
;           for (int kt = 0; kt < 4; ++kt)
; #pragma unroll
;             for (int j = 0; j < 4; ++j) { const float pv = __builtin_amdgcn_exp2f(__builtin_fmaf(s[kt][qt][j], c1, -m0)); s[kt][qt][j] = pv; sum += pv; }
;         }
;         lrun[qt] += sum;
;     ...
; #pragma unroll
;     for (int k2 = 0; k2 < 2; ++k2) {
;       bf16x8 pf[2];
; #pragma unroll
;       for (int qt = 0; qt < 2; ++qt) {
;         u32x4 u;
;         u[0] = cvt_pk_bf16(s[2 * k2][qt][0], s[2 * k2][qt][1]); u[1] = cvt_pk_bf16(s[2 * k2][qt][2], s[2 * k2][qt][3]);
;         u[2] = cvt_pk_bf16(s[2 * k2 + 1][qt][0], s[2 * k2 + 1][qt][1]); u[3] = cvt_pk_bf16(s[2 * k2 + 1][qt][2], s[2 * k2 + 1][qt][3]);
;         pf[qt] = __builtin_bit_cast(bf16x8, u);
;       }
; #pragma unroll
;       for (int d = 0; d < 4; ++d) {
;         o[d][0] = __builtin_amdgcn_mfma_f32_16x16x32_bf16(vfr[k2][d], pf[0], o[d][0], 0, 0, 0);
;         o[d][1] = __builtin_amdgcn_mfma_f32_16x16x32_bf16(vfr[k2][d], pf[1], o[d][1], 0, 0, 0);
;       }
.LBB0_1073:
	s_andn2_b64 vcc, exec, s[0:1]
	s_cbranch_vccnz .LBB0_1075
	v_subrev_u32_e32 v2, 47, v208
	s_movk_i32 s101, 0x100
	v_lshl_add_u32 v211, v2, 2, s101
	ds_read_b32 v132, v211 offset:41728
	ds_read_b32 v133, v211 offset:41732
	ds_read_b32 v134, v211 offset:41736
	ds_read_b32 v135, v211 offset:41740
	ds_read_b32 v136, v211 offset:41792
	ds_read_b32 v137, v211 offset:41796
	ds_read_b32 v138, v211 offset:41800
	ds_read_b32 v139, v211 offset:41804
	ds_read_b32 v140, v211 offset:41856
	ds_read_b32 v141, v211 offset:41860
	ds_read_b32 v142, v211 offset:41864
	ds_read_b32 v143, v211 offset:41868
	ds_read_b32 v144, v211 offset:41920
	s_add_i32 s0, s19, s43
	s_waitcnt lgkmcnt(12)
	s_add_i32 s26, s0, -4
	ds_read_b32 v145, v211 offset:41924
	v_fmac_f32_e32 v132, 0x3e38aa3b, v124
	s_waitcnt lgkmcnt(12)
	v_cmp_ge_i32_e64 s[0:1], s26, v164
	v_cmp_lt_i32_e32 vcc, s26, v163
	v_exp_f32_e32 v124, v132
	v_fmac_f32_e32 v133, 0x3e38aa3b, v125
	s_or_b64 s[0:1], vcc, s[0:1]
	v_exp_f32_e32 v125, v133
	s_or_b64 s[26:27], s[0:1], s[82:83]
	ds_read_b32 v3, v211 offset:41928
	ds_read_b32 v147, v211 offset:41932
	v_cndmask_b32_e64 v132, v124, 0, s[26:27]
	s_or_b64 s[26:27], s[0:1], s[74:75]
	v_cndmask_b32_e64 v133, v125, 0, s[26:27]
	s_waitcnt lgkmcnt(13)
	v_fma_f32 v125, v126, s62, v134
	v_exp_f32_e32 v125, v125
	s_or_b64 s[26:27], s[0:1], s[76:77]
	v_cndmask_b32_e64 v134, v125, 0, s[26:27]
	s_or_b64 s[26:27], s[0:1], s[78:79]
	s_waitcnt lgkmcnt(12)
	v_fma_f32 v125, v127, s62, v135
	v_exp_f32_e32 v125, v125
	s_nop 0
	v_cndmask_b32_e64 v135, v125, 0, s[26:27]
	s_or_b64 s[26:27], s[0:1], s[80:81]
	s_waitcnt lgkmcnt(1)
	v_fma_f32 v125, v120, s62, v136
	v_exp_f32_e32 v120, v125
	v_cndmask_b32_e64 v124, v178, 0, s[26:27]
	s_or_b64 s[26:27], s[0:1], s[84:85]
	v_fmac_f32_e32 v3, 0x3e38aa3b, v102
	v_mul_f32_e32 v136, v124, v120
	v_fma_f32 v124, v121, s62, v137
	v_exp_f32_e32 v121, v124
	v_cndmask_b32_e64 v120, v179, 0, s[26:27]
	s_or_b64 s[26:27], s[0:1], s[86:87]
	v_exp_f32_e32 v3, v3
	v_mul_f32_e32 v137, v120, v121
	v_fma_f32 v121, v122, s62, v138
	v_exp_f32_e32 v121, v121
	v_cndmask_b32_e64 v120, v180, 0, s[26:27]
	s_or_b64 s[26:27], s[0:1], s[88:89]
	v_mul_f32_e32 v138, v120, v121
	v_fma_f32 v121, v123, s62, v139
	v_exp_f32_e32 v121, v121
	v_cndmask_b32_e64 v120, v181, 0, s[26:27]
	s_or_b64 s[26:27], s[0:1], s[90:91]
	v_mul_f32_e32 v139, v120, v121
	v_fma_f32 v121, v116, s62, v140
	v_exp_f32_e32 v116, v121
	v_cndmask_b32_e64 v120, v182, 0, s[26:27]
	s_or_b64 s[26:27], s[0:1], s[92:93]
	v_mul_f32_e32 v140, v120, v116
	v_fma_f32 v120, v117, s62, v141
	v_exp_f32_e32 v117, v120
	v_cndmask_b32_e64 v116, v183, 0, s[26:27]
	s_or_b64 s[26:27], s[0:1], s[94:95]
	v_mul_f32_e32 v141, v116, v117
	v_fma_f32 v117, v118, s62, v142
	v_exp_f32_e32 v117, v117
	v_cndmask_b32_e64 v116, v184, 0, s[26:27]
	s_or_b64 s[26:27], s[0:1], s[96:97]
	v_mul_f32_e32 v142, v116, v117
	v_fma_f32 v117, v119, s62, v143
	v_exp_f32_e32 v117, v117
	v_cndmask_b32_e64 v116, v185, 0, s[26:27]
	v_mul_f32_e32 v143, v116, v117
	v_fma_f32 v117, v100, s62, v144
	v_exp_f32_e32 v100, v117
	v_cndmask_b32_e64 v116, v186, 0, s[0:1]
	v_mul_f32_e32 v144, v116, v100
	v_fma_f32 v116, v101, s62, v145
	v_exp_f32_e32 v101, v116
	v_cndmask_b32_e64 v100, v187, 0, s[0:1]
	v_mul_f32_e32 v145, v100, v101
	v_cndmask_b32_e64 v100, v189, 0, s[0:1]
	v_mul_f32_e32 v146, v100, v3
	s_waitcnt lgkmcnt(0)
	v_fma_f32 v100, v103, s62, v147
	v_exp_f32_e32 v100, v100
	v_cndmask_b32_e64 v3, v203, 0, s[0:1]
	v_mul_f32_e32 v147, v3, v100
.LBB0_1075:
	v_pk_add_f32 v[100:101], v[104:105], v[106:107]
	v_pk_add_f32 v[102:103], v[132:133], v[134:135]
	v_pk_add_f32 v[100:101], v[100:101], v[108:109]
	v_pk_add_f32 v[102:103], v[102:103], v[136:137]
	v_pk_add_f32 v[100:101], v[100:101], v[110:111]
	v_pk_add_f32 v[102:103], v[102:103], v[138:139]
	v_pk_add_f32 v[100:101], v[100:101], v[112:113]
	v_pk_add_f32 v[102:103], v[102:103], v[140:141]
	v_pk_add_f32 v[100:101], v[100:101], v[114:115]
	v_pk_add_f32 v[102:103], v[102:103], v[142:143]
	v_pk_add_f32 v[100:101], v[100:101], v[128:129]
	v_pk_add_f32 v[102:103], v[102:103], v[144:145]
	v_pk_add_f32 v[100:101], v[100:101], v[130:131]
	v_pk_add_f32 v[102:103], v[102:103], v[146:147]
	v_add_f32_e32 v0, v100, v101
	v_add_f32_e32 v2, v102, v103
	v_cvt_pk_bf16_f32 v100, v104, v105
	v_cvt_pk_bf16_f32 v101, v106, v107
	v_cvt_pk_bf16_f32 v102, v108, v109
	v_cvt_pk_bf16_f32 v103, v110, v111
	v_cvt_pk_bf16_f32 v104, v132, v133
	v_cvt_pk_bf16_f32 v105, v134, v135
	v_cvt_pk_bf16_f32 v106, v136, v137
	v_cvt_pk_bf16_f32 v107, v138, v139
	s_waitcnt lgkmcnt(13)
	v_mfma_f32_16x16x32_bf16 v[64:67], v[72:75], v[100:103], v[64:67]
	s_cmp_lt_i32 s43, s42
	s_cselect_b64 s[0:1], -1, 0
	s_cmp_ge_i32 s43, s42
	v_mfma_f32_16x16x32_bf16 v[48:51], v[72:75], v[104:107], v[48:51]
	v_cvt_pk_bf16_f32 v72, v140, v141
	v_cvt_pk_bf16_f32 v73, v142, v143
	v_cvt_pk_bf16_f32 v74, v144, v145
	s_waitcnt lgkmcnt(12)
	v_mfma_f32_16x16x32_bf16 v[60:63], v[68:71], v[100:103], v[60:63]
	v_cvt_pk_bf16_f32 v75, v146, v147
	v_mfma_f32_16x16x32_bf16 v[12:15], v[68:71], v[104:107], v[12:15]
	v_cvt_pk_bf16_f32 v68, v112, v113
	v_cvt_pk_bf16_f32 v69, v114, v115
	v_cvt_pk_bf16_f32 v70, v128, v129
	s_waitcnt lgkmcnt(10)
	v_mfma_f32_16x16x32_bf16 v[56:59], v[80:83], v[100:103], v[56:59]
	v_cvt_pk_bf16_f32 v71, v130, v131
	v_mfma_f32_16x16x32_bf16 v[8:11], v[80:83], v[104:107], v[8:11]
	s_waitcnt lgkmcnt(8)
	v_mfma_f32_16x16x32_bf16 v[52:55], v[88:91], v[100:103], v[52:55]
	v_mfma_f32_16x16x32_bf16 v[4:7], v[88:91], v[104:107], v[4:7]
	s_waitcnt lgkmcnt(6)
	v_mfma_f32_16x16x32_bf16 v[64:67], v[76:79], v[68:71], v[64:67]
	v_mfma_f32_16x16x32_bf16 v[48:51], v[76:79], v[72:75], v[48:51]
	s_waitcnt lgkmcnt(4)
	v_mfma_f32_16x16x32_bf16 v[60:63], v[84:87], v[68:71], v[60:63]
	v_mfma_f32_16x16x32_bf16 v[12:15], v[84:87], v[72:75], v[12:15]
	s_waitcnt lgkmcnt(2)
	v_mfma_f32_16x16x32_bf16 v[56:59], v[96:99], v[68:71], v[56:59]
	v_mfma_f32_16x16x32_bf16 v[8:11], v[96:99], v[72:75], v[8:11]
	s_waitcnt lgkmcnt(0)
	v_mfma_f32_16x16x32_bf16 v[52:55], v[92:95], v[68:71], v[52:55]
	v_mfma_f32_16x16x32_bf16 v[4:7], v[92:95], v[72:75], v[4:7]
	s_cbranch_scc1 .LBB0_1079
	s_and_saveexec_b64 s[26:27], s[48:49]
	s_cbranch_execz .LBB0_1078
	v_add_u32_e32 v3, v204, v205
	s_waitcnt vmcnt(1)
	ds_write_b128 v3, v[40:43] offset:20480

; template <int DQK, bool NA, bool SMAX, int LDV> ...
;     ...
;         if (NA && it >= 4) {
;           const int kr = rs + (it - 4);
;           const int ql = w * 32 + qt * 16 + fr, qr = r0 + (ql >> 6), qc = ql & 63;
;           const int rst = min(max(qr - 4, 0), 24);
;           const bool rowok = (kr >= rst) && (kr < rst + 8);
;           const int cst = min(max(qc - 8, 0), 48);
;           const int base = (kr - qr + 7) * 31 + 15 - qc;
;           float bv[4][4];
; #pragma unroll
;           for (int kt = 0; kt < 4; ++kt)
; #pragma unroll
;             for (int j = 0; j < 4; ++j) bv[kt][j] = rpbl[min(max(base + kt * 16 + fq * 4 + j, 0), 464)];
; #pragma unroll
;           for (int kt = 0; kt < 4; ++kt)
; #pragma unroll
;             for (int j = 0; j < 4; ++j) {
;               const int kc = kt * 16 + fq * 4 + j;
;               const float okf = (rowok && (kc >= cst) && (kc < cst + 16)) ? 1.f : 0.f;
;               const float pv = __builtin_amdgcn_exp2f(__builtin_fmaf(s[kt][qt][j], c1, bv[kt][j] - m0)) * okf;
;               s[kt][qt][j] = pv; sum += pv;
;             }
.LBB0_1085:
	s_movk_i32 s101, 0x100
	v_lshl_add_u32 v211, v208, 2, s101
	ds_read_b32 v0, v211 offset:41728
	ds_read_b32 v105, v211 offset:41732
	ds_read_b32 v3, v211 offset:41932
	ds_read_b32 v106, v211 offset:41736
	s_add_i32 s0, s19, s43
	s_add_i32 s0, s0, -3
	v_cmp_ge_i32_e32 vcc, s0, v164
	v_cmp_lt_i32_e64 s[0:1], s0, v163
	s_waitcnt lgkmcnt(3)
	ds_read_b32 v107, v211 offset:41740
	s_or_b64 s[0:1], s[0:1], vcc
	v_fmac_f32_e32 v0, 0x3e38aa3b, v144
	s_waitcnt lgkmcnt(3)
	s_or_b64 s[26:27], s[0:1], s[58:59]
	v_exp_f32_e32 v0, v0
	v_fmac_f32_e32 v105, 0x3e38aa3b, v145
	v_cndmask_b32_e64 v104, v0, 0, s[26:27]
	v_readlane_b32 s26, v248, 21
	v_exp_f32_e32 v131, v105
	v_readlane_b32 s27, v248, 22
	ds_read_b32 v108, v211 offset:41792
	s_or_b64 s[26:27], s[0:1], s[26:27]
	s_waitcnt lgkmcnt(2)
	v_cndmask_b32_e64 v105, v131, 0, s[26:27]
	v_fmac_f32_e32 v106, 0x3e38aa3b, v146
	v_exp_f32_e32 v131, v106
	ds_read_b32 v109, v211 offset:41796
	s_or_b64 s[26:27], s[0:1], s[52:53]
	s_waitcnt lgkmcnt(2)
	v_cndmask_b32_e64 v106, v131, 0, s[26:27]
	v_fmac_f32_e32 v107, 0x3e38aa3b, v147
	v_exp_f32_e32 v131, v107
	ds_read_b32 v110, v211 offset:41800
	s_or_b64 s[26:27], s[0:1], s[54:55]
	s_waitcnt lgkmcnt(2)
	v_cndmask_b32_e64 v107, v131, 0, s[26:27]
	v_fmac_f32_e32 v108, 0x3e38aa3b, v140
	v_exp_f32_e32 v131, v108
	ds_read_b32 v111, v211 offset:41804
	s_or_b64 s[26:27], s[0:1], s[56:57]
	s_waitcnt lgkmcnt(2)
	v_cndmask_b32_e64 v130, v165, 0, s[26:27]
	v_fmac_f32_e32 v109, 0x3e38aa3b, v141
	v_mul_f32_e32 v108, v130, v131
	v_exp_f32_e32 v131, v109
	ds_read_b32 v112, v211 offset:41856
	s_or_b64 s[26:27], s[0:1], s[60:61]
	s_waitcnt lgkmcnt(2)
	v_cndmask_b32_e64 v130, v166, 0, s[26:27]
	v_fmac_f32_e32 v110, 0x3e38aa3b, v142
	v_mul_f32_e32 v109, v130, v131
	v_exp_f32_e32 v131, v110
	ds_read_b32 v113, v211 offset:41860
	s_or_b64 s[26:27], s[0:1], s[50:51]
	s_waitcnt lgkmcnt(2)
	v_cndmask_b32_e64 v130, v168, 0, s[26:27]
	v_fmac_f32_e32 v111, 0x3e38aa3b, v143
	v_mul_f32_e32 v110, v130, v131
	v_exp_f32_e32 v131, v111
	ds_read_b32 v114, v211 offset:41864
	s_or_b64 s[26:27], s[0:1], s[64:65]
	s_waitcnt lgkmcnt(2)
	v_cndmask_b32_e64 v130, v169, 0, s[26:27]
	v_fmac_f32_e32 v112, 0x3e38aa3b, v136
	v_mul_f32_e32 v111, v130, v131
	v_exp_f32_e32 v131, v112
	ds_read_b32 v115, v211 offset:41868
	s_or_b64 s[26:27], s[0:1], s[66:67]
	s_waitcnt lgkmcnt(2)
	v_cndmask_b32_e64 v130, v170, 0, s[26:27]
	v_fmac_f32_e32 v113, 0x3e38aa3b, v137
	v_mul_f32_e32 v112, v130, v131
	v_exp_f32_e32 v131, v113
	ds_read_b32 v128, v211 offset:41920
	s_or_b64 s[26:27], s[0:1], s[68:69]
	s_waitcnt lgkmcnt(2)
	v_cndmask_b32_e64 v130, v171, 0, s[26:27]
	v_fmac_f32_e32 v114, 0x3e38aa3b, v138
	v_mul_f32_e32 v113, v130, v131
	v_exp_f32_e32 v131, v114
	ds_read_b32 v129, v211 offset:41924
	s_or_b64 s[26:27], s[0:1], s[70:71]
	s_waitcnt lgkmcnt(2)
	v_cndmask_b32_e64 v130, v172, 0, s[26:27]
	v_fmac_f32_e32 v115, 0x3e38aa3b, v139
	v_mul_f32_e32 v114, v130, v131
	v_exp_f32_e32 v131, v115
	ds_read_b32 v2, v211 offset:41928
	s_or_b64 s[26:27], s[0:1], s[72:73]
	s_waitcnt lgkmcnt(2)
	v_cndmask_b32_e64 v130, v173, 0, s[26:27]
	v_fmac_f32_e32 v128, 0x3e38aa3b, v132
	v_mul_f32_e32 v115, v130, v131
	v_exp_f32_e32 v131, v128
	s_waitcnt lgkmcnt(1)
	v_cndmask_b32_e64 v130, v174, 0, s[0:1]
	v_fmac_f32_e32 v129, 0x3e38aa3b, v133
	s_waitcnt lgkmcnt(0)
	v_mul_f32_e32 v128, v130, v131
	v_exp_f32_e32 v131, v129
	v_fmac_f32_e32 v2, 0x3e38aa3b, v134
	v_exp_f32_e32 v2, v2
	v_fmac_f32_e32 v3, 0x3e38aa3b, v135
	v_exp_f32_e32 v3, v3
	v_cndmask_b32_e64 v130, v175, 0, s[0:1]
	v_mul_f32_e32 v129, v130, v131
	v_cndmask_b32_e64 v131, v176, 0, s[0:1]
	v_mul_f32_e32 v130, v131, v2
	v_cndmask_b32_e64 v2, v177, 0, s[0:1]
	v_mul_f32_e32 v131, v2, v3

; DI unsigned cvt_pk_bf16(float lo, float hi) { f32x2_t v = {lo, hi}; bf16x2_t b = __builtin_convertvector(v, bf16x2_t); return __builtin_bit_cast(unsigned, b); }
; template <int DQK, bool NA, bool SMAX, int LDV> ...
;     ...
;           for (int kt = 0; kt < 4; ++kt)
; #pragma unroll
;             for (int j = 0; j < 4; ++j) bv[kt][j] = rpbl[min(max(base + kt * 16 + fq * 4 + j, 0), 464)];
; #pragma unroll
;           for (int kt = 0; kt < 4; ++kt)
; #pragma unroll
;             for (int j = 0; j < 4; ++j) {
;               const int kc = kt * 16 + fq * 4 + j;
;               const float okf = (rowok && (kc >= cst) && (kc < cst + 16)) ? 1.f : 0.f;
;               const float pv = __builtin_amdgcn_exp2f(__builtin_fmaf(s[kt][qt][j], c1, bv[kt][j] - m0)) * okf;
;               s[kt][qt][j] = pv; sum += pv;
;             }
;         } else {
; #pragma unroll
;           for (int kt = 0; kt < 4; ++kt)
; #pragma unroll
;             for (int j = 0; j < 4; ++j) { const float pv = __builtin_amdgcn_exp2f(__builtin_fmaf(s[kt][qt][j], c1, -m0)); s[kt][qt][j] = pv; sum += pv; }
;         }
;         lrun[qt] += sum;
;     ...
; #pragma unroll
;     for (int k2 = 0; k2 < 2; ++k2) {
;       bf16x8 pf[2];
; #pragma unroll
;       for (int qt = 0; qt < 2; ++qt) {
;         u32x4 u;
;         u[0] = cvt_pk_bf16(s[2 * k2][qt][0], s[2 * k2][qt][1]); u[1] = cvt_pk_bf16(s[2 * k2][qt][2], s[2 * k2][qt][3]);
;         u[2] = cvt_pk_bf16(s[2 * k2 + 1][qt][0], s[2 * k2 + 1][qt][1]); u[3] = cvt_pk_bf16(s[2 * k2 + 1][qt][2], s[2 * k2 + 1][qt][3]);
;         pf[qt] = __builtin_bit_cast(bf16x8, u);
;       }
; #pragma unroll
;       for (int d = 0; d < 4; ++d) {
;         o[d][0] = __builtin_amdgcn_mfma_f32_16x16x32_bf16(vfr[k2][d], pf[0], o[d][0], 0, 0, 0);
;         o[d][1] = __builtin_amdgcn_mfma_f32_16x16x32_bf16(vfr[k2][d], pf[1], o[d][1], 0, 0, 0);
;       }
.LBB0_1089:
	v_add_u32_e32 v2, -16, v208
	s_movk_i32 s101, 0x100
	v_lshl_add_u32 v211, v2, 2, s101
	ds_read_b32 v132, v211 offset:41728
	ds_read_b32 v133, v211 offset:41732
	ds_read_b32 v134, v211 offset:41736
	ds_read_b32 v135, v211 offset:41740
	ds_read_b32 v136, v211 offset:41792
	ds_read_b32 v137, v211 offset:41796
	ds_read_b32 v138, v211 offset:41800
	ds_read_b32 v139, v211 offset:41804
	ds_read_b32 v140, v211 offset:41856
	ds_read_b32 v141, v211 offset:41860
	ds_read_b32 v142, v211 offset:41864
	ds_read_b32 v143, v211 offset:41868
	ds_read_b32 v144, v211 offset:41920
	s_add_i32 s0, s19, s43
	s_waitcnt lgkmcnt(12)
	s_add_i32 s0, s0, -3
	ds_read_b32 v145, v211 offset:41924
	v_fmac_f32_e32 v132, 0x3e38aa3b, v124
	s_waitcnt lgkmcnt(12)
	v_cmp_ge_i32_e32 vcc, s0, v164
	v_cmp_lt_i32_e64 s[0:1], s0, v163
	v_exp_f32_e32 v124, v132
	v_fmac_f32_e32 v133, 0x3e38aa3b, v125
	s_or_b64 s[0:1], s[0:1], vcc
	v_exp_f32_e32 v125, v133
	s_or_b64 s[26:27], s[0:1], s[82:83]
	ds_read_b32 v3, v211 offset:41928
	ds_read_b32 v147, v211 offset:41932
	v_cndmask_b32_e64 v132, v124, 0, s[26:27]
	s_or_b64 s[26:27], s[0:1], s[74:75]
	v_cndmask_b32_e64 v133, v125, 0, s[26:27]
	s_waitcnt lgkmcnt(13)
	v_fma_f32 v125, v126, s62, v134
	v_exp_f32_e32 v125, v125
	s_or_b64 s[26:27], s[0:1], s[76:77]
	v_cndmask_b32_e64 v134, v125, 0, s[26:27]
	s_or_b64 s[26:27], s[0:1], s[78:79]
	s_waitcnt lgkmcnt(12)
	v_fma_f32 v125, v127, s62, v135
	v_exp_f32_e32 v125, v125
	s_nop 0
	v_cndmask_b32_e64 v135, v125, 0, s[26:27]
	s_or_b64 s[26:27], s[0:1], s[80:81]
	s_waitcnt lgkmcnt(1)
	v_fma_f32 v125, v120, s62, v136
	v_exp_f32_e32 v120, v125
	v_cndmask_b32_e64 v124, v178, 0, s[26:27]
	s_or_b64 s[26:27], s[0:1], s[84:85]
	v_fmac_f32_e32 v3, 0x3e38aa3b, v102
	v_mul_f32_e32 v136, v124, v120
	v_fma_f32 v124, v121, s62, v137
	v_exp_f32_e32 v121, v124
	v_cndmask_b32_e64 v120, v179, 0, s[26:27]
	s_or_b64 s[26:27], s[0:1], s[86:87]
	v_exp_f32_e32 v3, v3
	v_mul_f32_e32 v137, v120, v121
	v_fma_f32 v121, v122, s62, v138
	v_exp_f32_e32 v121, v121
	v_cndmask_b32_e64 v120, v180, 0, s[26:27]
	s_or_b64 s[26:27], s[0:1], s[88:89]
	v_mul_f32_e32 v138, v120, v121
	v_fma_f32 v121, v123, s62, v139
	v_exp_f32_e32 v121, v121
	v_cndmask_b32_e64 v120, v181, 0, s[26:27]
	s_or_b64 s[26:27], s[0:1], s[90:91]
	v_mul_f32_e32 v139, v120, v121
	v_fma_f32 v121, v116, s62, v140
	v_exp_f32_e32 v116, v121
	v_cndmask_b32_e64 v120, v182, 0, s[26:27]
	s_or_b64 s[26:27], s[0:1], s[92:93]
	v_mul_f32_e32 v140, v120, v116
	v_fma_f32 v120, v117, s62, v141
	v_exp_f32_e32 v117, v120
	v_cndmask_b32_e64 v116, v183, 0, s[26:27]
	s_or_b64 s[26:27], s[0:1], s[94:95]
	v_mul_f32_e32 v141, v116, v117
	v_fma_f32 v117, v118, s62, v142
	v_exp_f32_e32 v117, v117
	v_cndmask_b32_e64 v116, v184, 0, s[26:27]
	s_or_b64 s[26:27], s[0:1], s[96:97]
	v_mul_f32_e32 v142, v116, v117
	v_fma_f32 v117, v119, s62, v143
	v_exp_f32_e32 v117, v117
	v_cndmask_b32_e64 v116, v185, 0, s[26:27]
	v_mul_f32_e32 v143, v116, v117
	v_fma_f32 v117, v100, s62, v144
	v_exp_f32_e32 v100, v117
	v_cndmask_b32_e64 v116, v186, 0, s[0:1]
	v_mul_f32_e32 v144, v116, v100
	v_fma_f32 v116, v101, s62, v145
	v_exp_f32_e32 v101, v116
	v_cndmask_b32_e64 v100, v187, 0, s[0:1]
	v_mul_f32_e32 v145, v100, v101
	v_cndmask_b32_e64 v100, v189, 0, s[0:1]
	v_mul_f32_e32 v146, v100, v3
	s_waitcnt lgkmcnt(0)
	v_fma_f32 v100, v103, s62, v147
	v_exp_f32_e32 v100, v100
	v_cndmask_b32_e64 v3, v203, 0, s[0:1]
	v_mul_f32_e32 v147, v3, v100
.LBB0_1090:
	v_pk_add_f32 v[100:101], v[104:105], v[106:107]
	v_pk_add_f32 v[102:103], v[132:133], v[134:135]
	v_pk_add_f32 v[100:101], v[100:101], v[108:109]
	v_pk_add_f32 v[102:103], v[102:103], v[136:137]
	v_pk_add_f32 v[100:101], v[100:101], v[110:111]
	v_pk_add_f32 v[102:103], v[102:103], v[138:139]
	v_pk_add_f32 v[100:101], v[100:101], v[112:113]
	v_pk_add_f32 v[102:103], v[102:103], v[140:141]
	v_pk_add_f32 v[100:101], v[100:101], v[114:115]
	v_pk_add_f32 v[102:103], v[102:103], v[142:143]
	v_pk_add_f32 v[100:101], v[100:101], v[128:129]
	v_pk_add_f32 v[102:103], v[102:103], v[144:145]
	v_pk_add_f32 v[100:101], v[100:101], v[130:131]
	v_pk_add_f32 v[102:103], v[102:103], v[146:147]
	v_add_f32_e32 v0, v100, v101
	v_add_f32_e32 v2, v102, v103
	v_cvt_pk_bf16_f32 v100, v104, v105
	v_cvt_pk_bf16_f32 v101, v106, v107
	v_cvt_pk_bf16_f32 v102, v108, v109
	v_cvt_pk_bf16_f32 v103, v110, v111
	v_cvt_pk_bf16_f32 v104, v132, v133
	v_cvt_pk_bf16_f32 v105, v134, v135
	v_cvt_pk_bf16_f32 v106, v136, v137
	v_cvt_pk_bf16_f32 v107, v138, v139
	s_waitcnt lgkmcnt(13)
	v_mfma_f32_16x16x32_bf16 v[64:67], v[72:75], v[100:103], v[64:67]
	s_cmp_ge_i32 s43, s33
	v_mfma_f32_16x16x32_bf16 v[48:51], v[72:75], v[104:107], v[48:51]
	v_cvt_pk_bf16_f32 v72, v140, v141
	v_cvt_pk_bf16_f32 v73, v142, v143
	v_cvt_pk_bf16_f32 v74, v144, v145
	s_waitcnt lgkmcnt(12)
	v_mfma_f32_16x16x32_bf16 v[60:63], v[68:71], v[100:103], v[60:63]
	v_cvt_pk_bf16_f32 v75, v146, v147
	v_mfma_f32_16x16x32_bf16 v[12:15], v[68:71], v[104:107], v[12:15]
	v_cvt_pk_bf16_f32 v68, v112, v113
	v_cvt_pk_bf16_f32 v69, v114, v115
	v_cvt_pk_bf16_f32 v70, v128, v129
	s_waitcnt lgkmcnt(10)
	v_mfma_f32_16x16x32_bf16 v[56:59], v[80:83], v[100:103], v[56:59]
	v_cvt_pk_bf16_f32 v71, v130, v131
	v_mfma_f32_16x16x32_bf16 v[8:11], v[80:83], v[104:107], v[8:11]
	s_waitcnt lgkmcnt(8)
	v_mfma_f32_16x16x32_bf16 v[52:55], v[88:91], v[100:103], v[52:55]
	v_mfma_f32_16x16x32_bf16 v[4:7], v[88:91], v[104:107], v[4:7]
	s_waitcnt lgkmcnt(6)
	v_mfma_f32_16x16x32_bf16 v[64:67], v[76:79], v[68:71], v[64:67]
	v_mfma_f32_16x16x32_bf16 v[48:51], v[76:79], v[72:75], v[48:51]
	s_waitcnt lgkmcnt(4)
	v_mfma_f32_16x16x32_bf16 v[60:63], v[84:87], v[68:71], v[60:63]
	v_mfma_f32_16x16x32_bf16 v[12:15], v[84:87], v[72:75], v[12:15]
	s_waitcnt lgkmcnt(2)
	v_mfma_f32_16x16x32_bf16 v[56:59], v[92:95], v[68:71], v[56:59]
	v_mfma_f32_16x16x32_bf16 v[8:11], v[92:95], v[72:75], v[8:11]
	s_waitcnt lgkmcnt(0)
	v_mfma_f32_16x16x32_bf16 v[52:55], v[96:99], v[68:71], v[52:55]
	v_mfma_f32_16x16x32_bf16 v[4:7], v[96:99], v[72:75], v[4:7]
	s_cbranch_scc1 .LBB0_1094
	s_and_saveexec_b64 s[0:1], s[48:49]
	s_cbranch_execz .LBB0_1093
	v_add_u32_e32 v3, v204, v205
	s_waitcnt vmcnt(1)
	ds_write_b128 v3, v[32:35]
